# EpiResid epilogue of the down GEMM: gate loaded once, row pointers derived by constant increments, source loads of 3 rows in flight
# baseline (speedup 1.0000x reference)
;   DI void operator()(const pg8::f32x4 (&acc)[2][2][4][2], const pg8::Unit& u, int wr, int wc, int fr, int fq) const {
;     const int row0 = u.pm * 256 + wr * 64 + fr, col0 = u.pn * 256 + wc * 32 + 8 * fq;
;     const int b = (u.pm * 256) / TT;
; #pragma unroll
;     for (int ai = 0; ai < 2; ++ai)
; #pragma unroll
;       for (int m = 0; m < 4; ++m) {
;         const int row = row0 + ai * 128 + m * 16;
;         const int t = row - b * TT;
;         const bool isc = t >= TL;
;         float* dst = isc ? xc + ((size_t)b * TC + (t - TL)) * DM : xout + ((size_t)b * TL + t) * DM;
;         const float* src = src_input ? (isc ? cin + ((size_t)b * TC + (t - TL)) * DM : xin + ((size_t)b * TL + t) * DM) : dst;
;         const float* gate = modl + (size_t)(isc ? 16 : b) * 6144 + gi * DM;
; #pragma unroll
;         for (int bj = 0; bj < 2; ++bj) {
;           const int col = col0 + bj * 128;
; #pragma unroll
;           for (int n = 0; n < 2; ++n) {
;             pg8::f32x4 sv = *(const pg8::f32x4*)(src + col + 4 * n);
;             pg8::f32x4 gv = *(const pg8::f32x4*)(gate + col + 4 * n);
;             pg8::f32x4 o = sv + gv * acc[ai][bj][m][n];
;             *(pg8::f32x4*)(dst + col + 4 * n) = o;
;           }
;         }
;       }
;   }
.LBB0_1507:
	s_mov_b32 s4, 0x38e38e39
	v_mul_hi_i32 v142, v148, s4
	v_lshrrev_b32_e32 v144, 31, v142
	v_ashrrev_i32_e32 v142, 1, v142
	v_add_u32_e32 v142, v142, v144
	s_movk_i32 s4, 0xf700
	s_load_dwordx4 s[24:27], s[0:1], 0x100
	v_lshlrev_b32_e32 v143, 8, v148
	v_mul_lo_u32 v144, v142, s4
	v_add_u32_e32 v143, v144, v143
	v_add_u32_e32 v160, v143, v154
	v_ashrrev_i32_e32 v143, 31, v142
	v_readlane_b32 s4, v252, 14
	s_movk_i32 s21, 0x7ff
	v_lshlrev_b64 v[144:145], 23, v[142:143]
	v_lshlrev_b64 v[146:147], 20, v[142:143]
	v_ashrrev_i32_e32 v143, 31, v160
	v_add_u32_e32 v148, 0xfffff800, v160
	v_readlane_b32 s5, v252, 15
	v_cmp_lt_i32_e32 vcc, s21, v160
	v_lshl_or_b32 v150, v149, 8, v156
	s_waitcnt lgkmcnt(0)
	v_lshl_add_u64 v[144:145], s[24:25], 0, v[144:145]
	v_lshl_add_u64 v[146:147], s[4:5], 0, v[146:147]
	v_cndmask_b32_e64 v149, v143, 0, vcc
	v_cndmask_b32_e32 v148, v160, v148, vcc
	v_cndmask_b32_e32 v163, v145, v147, vcc
	v_cndmask_b32_e32 v162, v144, v146, vcc
	v_lshlrev_b64 v[148:149], 12, v[148:149]
	v_lshl_add_u64 v[162:163], v[162:163], 0, v[148:149]
	v_cndmask_b32_e64 v143, v142, 16, vcc
	v_mov_b64_e32 v[148:149], s[10:11]
	s_movk_i32 s22, 0x6000
	v_ashrrev_i32_e32 v151, 31, v150
	v_mad_i64_i32 v[164:165], s[4:5], v143, s22, v[148:149]
	v_lshlrev_b64 v[150:151], 2, v[150:151]
	v_lshl_add_u64 v[176:177], v[164:165], 0, v[150:151]
	v_lshl_add_u64 v[174:175], v[162:163], 0, v[150:151]
	s_mov_b64 s[4:5], 0x10000
	s_mov_b64 s[24:25], 0x50000
	global_load_dwordx4 v[202:205], v[176:177], off
	global_load_dwordx4 v[206:209], v[176:177], off offset:16
	global_load_dwordx4 v[210:213], v[176:177], off offset:512
	global_load_dwordx4 v[214:217], v[176:177], off offset:528
	global_load_dwordx4 v[218:221], v[174:175], off
	global_load_dwordx4 v[222:225], v[174:175], off offset:16
	global_load_dwordx4 v[226:229], v[174:175], off offset:512
	global_load_dwordx4 v[230:233], v[174:175], off offset:528
	v_lshl_add_u64 v[142:143], v[174:175], 0, s[4:5]
	global_load_dwordx4 v[234:237], v[142:143], off
	global_load_dwordx4 v[238:241], v[142:143], off offset:16
	global_load_dwordx4 v[242:245], v[142:143], off offset:512
	global_load_dwordx4 v[246:249], v[142:143], off offset:528
	v_lshl_add_u64 v[144:145], v[142:143], 0, s[4:5]
	global_load_dwordx4 v[160:163], v[144:145], off
	global_load_dwordx4 v[164:167], v[144:145], off offset:16
	global_load_dwordx4 v[168:171], v[144:145], off offset:512
	global_load_dwordx4 v[178:181], v[144:145], off offset:528
	v_lshl_add_u64 v[146:147], v[144:145], 0, s[4:5]
	v_lshl_add_u64 v[148:149], v[146:147], 0, s[24:25]
	v_lshl_add_u64 v[150:151], v[148:149], 0, s[4:5]
	v_lshl_add_u64 v[192:193], v[150:151], 0, s[4:5]
	v_lshl_add_u64 v[194:195], v[192:193], 0, s[4:5]
	s_waitcnt vmcnt(8)
	v_pk_fma_f32 v[126:127], v[126:127], v[204:205], v[220:221]
	v_pk_fma_f32 v[124:125], v[124:125], v[202:203], v[218:219]
	v_pk_fma_f32 v[122:123], v[122:123], v[208:209], v[224:225]
	v_pk_fma_f32 v[120:121], v[120:121], v[206:207], v[222:223]
	v_pk_fma_f32 v[118:119], v[118:119], v[212:213], v[228:229]
	v_pk_fma_f32 v[116:117], v[116:117], v[210:211], v[226:227]
	v_pk_fma_f32 v[106:107], v[106:107], v[216:217], v[232:233]
	v_pk_fma_f32 v[104:105], v[104:105], v[214:215], v[230:231]
	global_store_dwordx4 v[174:175], v[124:127], off
	global_store_dwordx4 v[174:175], v[120:123], off offset:16
	global_store_dwordx4 v[174:175], v[116:119], off offset:512
	global_store_dwordx4 v[174:175], v[104:107], off offset:528
	global_load_dwordx4 v[218:221], v[146:147], off
	global_load_dwordx4 v[222:225], v[146:147], off offset:16
	global_load_dwordx4 v[226:229], v[146:147], off offset:512
	global_load_dwordx4 v[230:233], v[146:147], off offset:528
	s_waitcnt vmcnt(12)
	v_pk_fma_f32 v[114:115], v[114:115], v[204:205], v[236:237]
	v_pk_fma_f32 v[112:113], v[112:113], v[202:203], v[234:235]
	v_pk_fma_f32 v[110:111], v[110:111], v[208:209], v[240:241]
	v_pk_fma_f32 v[108:109], v[108:109], v[206:207], v[238:239]
	v_pk_fma_f32 v[102:103], v[102:103], v[212:213], v[244:245]
	v_pk_fma_f32 v[100:101], v[100:101], v[210:211], v[242:243]
	v_pk_fma_f32 v[90:91], v[90:91], v[216:217], v[248:249]
	v_pk_fma_f32 v[88:89], v[88:89], v[214:215], v[246:247]
	global_store_dwordx4 v[142:143], v[112:115], off
	global_store_dwordx4 v[142:143], v[108:111], off offset:16
	global_store_dwordx4 v[142:143], v[100:103], off offset:512
	global_store_dwordx4 v[142:143], v[88:91], off offset:528
	global_load_dwordx4 v[234:237], v[148:149], off
	global_load_dwordx4 v[238:241], v[148:149], off offset:16
	global_load_dwordx4 v[242:245], v[148:149], off offset:512
	global_load_dwordx4 v[246:249], v[148:149], off offset:528
	s_waitcnt vmcnt(16)
;   DI void operator()(const pg8::f32x4 (&acc)[2][2][4][2], const pg8::Unit& u, int wr, int wc, int fr, int fq) const {
;     ...
; #pragma unroll
;     for (int ai = 0; ai < 2; ++ai)
; #pragma unroll
;       for (int m = 0; m < 4; ++m) {
;         const int row = row0 + ai * 128 + m * 16;
;         const int t = row - b * TT;
;         const bool isc = t >= TL;
;         float* dst = isc ? xc + ((size_t)b * TC + (t - TL)) * DM : xout + ((size_t)b * TL + t) * DM;
;         const float* src = src_input ? (isc ? cin + ((size_t)b * TC + (t - TL)) * DM : xin + ((size_t)b * TL + t) * DM) : dst;
;         const float* gate = modl + (size_t)(isc ? 16 : b) * 6144 + gi * DM;
; #pragma unroll
;         for (int bj = 0; bj < 2; ++bj) {
;           const int col = col0 + bj * 128;
; #pragma unroll
;           for (int n = 0; n < 2; ++n) {
;             pg8::f32x4 sv = *(const pg8::f32x4*)(src + col + 4 * n);
;             pg8::f32x4 gv = *(const pg8::f32x4*)(gate + col + 4 * n);
;             pg8::f32x4 o = sv + gv * acc[ai][bj][m][n];
;             *(pg8::f32x4*)(dst + col + 4 * n) = o;
;           }
;         }
;       }
;   }
	v_pk_fma_f32 v[98:99], v[98:99], v[204:205], v[162:163]
	v_pk_fma_f32 v[96:97], v[96:97], v[202:203], v[160:161]
	v_pk_fma_f32 v[94:95], v[94:95], v[208:209], v[166:167]
	v_pk_fma_f32 v[92:93], v[92:93], v[206:207], v[164:165]
	v_pk_fma_f32 v[86:87], v[86:87], v[212:213], v[170:171]
	v_pk_fma_f32 v[84:85], v[84:85], v[210:211], v[168:169]
	v_pk_fma_f32 v[74:75], v[74:75], v[216:217], v[180:181]
	v_pk_fma_f32 v[72:73], v[72:73], v[214:215], v[178:179]
	global_store_dwordx4 v[144:145], v[96:99], off
	global_store_dwordx4 v[144:145], v[92:95], off offset:16
	global_store_dwordx4 v[144:145], v[84:87], off offset:512
	global_store_dwordx4 v[144:145], v[72:75], off offset:528
	global_load_dwordx4 v[160:163], v[150:151], off
	global_load_dwordx4 v[164:167], v[150:151], off offset:16
	global_load_dwordx4 v[168:171], v[150:151], off offset:512
	global_load_dwordx4 v[178:181], v[150:151], off offset:528
	s_waitcnt vmcnt(16)
	v_pk_fma_f32 v[82:83], v[82:83], v[204:205], v[220:221]
	v_pk_fma_f32 v[80:81], v[80:81], v[202:203], v[218:219]
	v_pk_fma_f32 v[78:79], v[78:79], v[208:209], v[224:225]
	v_pk_fma_f32 v[76:77], v[76:77], v[206:207], v[222:223]
	v_pk_fma_f32 v[70:71], v[70:71], v[212:213], v[228:229]
	v_pk_fma_f32 v[68:69], v[68:69], v[210:211], v[226:227]
	v_pk_fma_f32 v[66:67], v[66:67], v[216:217], v[232:233]
	v_pk_fma_f32 v[64:65], v[64:65], v[214:215], v[230:231]
	global_store_dwordx4 v[146:147], v[80:83], off
	global_store_dwordx4 v[146:147], v[76:79], off offset:16
	global_store_dwordx4 v[146:147], v[68:71], off offset:512
	global_store_dwordx4 v[146:147], v[64:67], off offset:528
	global_load_dwordx4 v[218:221], v[192:193], off
	global_load_dwordx4 v[222:225], v[192:193], off offset:16
	global_load_dwordx4 v[226:229], v[192:193], off offset:512
	global_load_dwordx4 v[230:233], v[192:193], off offset:528
	s_waitcnt vmcnt(16)
	v_pk_fma_f32 v[62:63], v[62:63], v[204:205], v[236:237]
	v_pk_fma_f32 v[60:61], v[60:61], v[202:203], v[234:235]
	v_pk_fma_f32 v[58:59], v[58:59], v[208:209], v[240:241]
	v_pk_fma_f32 v[56:57], v[56:57], v[206:207], v[238:239]
	v_pk_fma_f32 v[54:55], v[54:55], v[212:213], v[244:245]
	v_pk_fma_f32 v[52:53], v[52:53], v[210:211], v[242:243]
	v_pk_fma_f32 v[42:43], v[42:43], v[216:217], v[248:249]
	v_pk_fma_f32 v[40:41], v[40:41], v[214:215], v[246:247]
	global_store_dwordx4 v[148:149], v[60:63], off
	global_store_dwordx4 v[148:149], v[56:59], off offset:16
	global_store_dwordx4 v[148:149], v[52:55], off offset:512
	global_store_dwordx4 v[148:149], v[40:43], off offset:528
	global_load_dwordx4 v[234:237], v[194:195], off
	global_load_dwordx4 v[238:241], v[194:195], off offset:16
	global_load_dwordx4 v[242:245], v[194:195], off offset:512
	global_load_dwordx4 v[246:249], v[194:195], off offset:528
	s_waitcnt vmcnt(16)
	v_pk_fma_f32 v[50:51], v[50:51], v[204:205], v[162:163]
	v_pk_fma_f32 v[48:49], v[48:49], v[202:203], v[160:161]
	v_pk_fma_f32 v[46:47], v[46:47], v[208:209], v[166:167]
	v_pk_fma_f32 v[44:45], v[44:45], v[206:207], v[164:165]
	v_pk_fma_f32 v[38:39], v[38:39], v[212:213], v[170:171]
	v_pk_fma_f32 v[36:37], v[36:37], v[210:211], v[168:169]
	v_pk_fma_f32 v[26:27], v[26:27], v[216:217], v[180:181]
	v_pk_fma_f32 v[24:25], v[24:25], v[214:215], v[178:179]
	global_store_dwordx4 v[150:151], v[48:51], off
	global_store_dwordx4 v[150:151], v[44:47], off offset:16
	global_store_dwordx4 v[150:151], v[36:39], off offset:512
	global_store_dwordx4 v[150:151], v[24:27], off offset:528
	s_waitcnt vmcnt(12)
	v_pk_fma_f32 v[34:35], v[34:35], v[204:205], v[220:221]
	v_pk_fma_f32 v[32:33], v[32:33], v[202:203], v[218:219]
	v_pk_fma_f32 v[30:31], v[30:31], v[208:209], v[224:225]
	v_pk_fma_f32 v[28:29], v[28:29], v[206:207], v[222:223]
	v_pk_fma_f32 v[22:23], v[22:23], v[212:213], v[228:229]
	v_pk_fma_f32 v[20:21], v[20:21], v[210:211], v[226:227]
	v_pk_fma_f32 v[10:11], v[10:11], v[216:217], v[232:233]
	v_pk_fma_f32 v[8:9], v[8:9], v[214:215], v[230:231]
	global_store_dwordx4 v[192:193], v[32:35], off
	global_store_dwordx4 v[192:193], v[28:31], off offset:16
	global_store_dwordx4 v[192:193], v[20:23], off offset:512
	global_store_dwordx4 v[192:193], v[8:11], off offset:528
	s_waitcnt vmcnt(8)
	v_pk_fma_f32 v[18:19], v[18:19], v[204:205], v[236:237]
	v_pk_fma_f32 v[16:17], v[16:17], v[202:203], v[234:235]
	v_pk_fma_f32 v[14:15], v[14:15], v[208:209], v[240:241]
	v_pk_fma_f32 v[12:13], v[12:13], v[206:207], v[238:239]
	v_pk_fma_f32 v[6:7], v[6:7], v[212:213], v[244:245]
	v_pk_fma_f32 v[4:5], v[4:5], v[210:211], v[242:243]
	v_pk_fma_f32 v[2:3], v[2:3], v[216:217], v[248:249]
	v_pk_fma_f32 v[0:1], v[0:1], v[214:215], v[246:247]
	global_store_dwordx4 v[194:195], v[16:19], off
	global_store_dwordx4 v[194:195], v[12:15], off offset:16
	global_store_dwordx4 v[194:195], v[4:7], off offset:512
	global_store_dwordx4 v[194:195], v[0:3], off offset:528
	s_and_b64 vcc, exec, s[2:3]
	s_mov_b64 s[2:3], -1
	s_cbranch_vccnz .LBB0_1496
	s_andn2_b64 vcc, exec, s[6:7]
	s_cbranch_vccnz .LBB0_1495
	s_barrier
	s_branch .LBB0_1495
